# mLSTM scan: next-chunk K/V row loads spread over the outputs phase (were one 18-load burst after a barrier); S=QK^T / CB^T fragment reads batched
# speedup vs baseline: 1.0278x; 1.0129x over previous
.LBB0_1841:
	s_bitcmp1_b32 s4, 0
	s_cselect_b32 s5, 0x610, 0
	s_add_i32 s33, s5, 0
	v_readlane_b32 s20, v234, 0
	s_add_i32 s33, s33, 0x1e400
	v_readlane_b32 s22, v234, 2
	v_readlane_b32 s23, v234, 3
	v_lshl_add_u32 v1, v170, 2, s33
	v_lshl_add_u32 v3, v168, 2, s33
	v_lshl_add_u32 v68, v197, 2, s33
	v_mov_b32_e32 v62, v200
	v_mov_b32_e32 v69, v201
	v_mov_b32_e32 v76, v202
	v_mov_b32_e32 v2, v203
	v_mov_b32_e32 v219, v204
	v_mov_b32_e32 v218, v205
	v_mov_b32_e32 v217, v212
	v_mov_b32_e32 v216, v169
	v_mov_b32_e32 v215, v213
	v_mov_b32_e32 v214, v199
	v_lshl_add_u64 v[60:61], s[22:23], 0, v[174:175]
	global_load_dwordx2 v[194:195], v[60:61], off offset:-64
	global_load_dwordx2 v[192:193], v[60:61], off offset:-32
	global_load_dwordx2 v[190:191], v[60:61], off
	global_load_dwordx2 v[186:187], v[60:61], off offset:32
	s_waitcnt vmcnt(13)
	ds_write_b128 v62, v[4:7]
	s_waitcnt vmcnt(12)
	ds_write_b128 v62, v[8:11] offset:34816
	s_waitcnt vmcnt(11)
	ds_write_b128 v62, v[12:15] offset:8704
	s_waitcnt vmcnt(10)
	ds_write_b128 v62, v[16:19] offset:43520
	s_waitcnt vmcnt(9)
	ds_write_b128 v62, v[20:23] offset:17408
	s_waitcnt vmcnt(8)
	ds_write_b128 v62, v[24:27] offset:52224
	s_waitcnt vmcnt(7)
	ds_write_b128 v62, v[28:31] offset:26112
	s_waitcnt vmcnt(6)
	ds_write_b128 v62, v[32:35] offset:60928
	ds_read_b32 v64, v68 offset:1024
	s_waitcnt vmcnt(5)
	v_lshlrev_b32_e32 v60, 16, v36
	v_and_b32_e32 v61, 0xffff0000, v36
	v_lshlrev_b32_e32 v62, 16, v37
	v_and_b32_e32 v63, 0xffff0000, v37
	s_waitcnt lgkmcnt(0)
	v_pk_mul_f32 v[60:61], v[64:65], v[60:61] op_sel_hi:[0,1]
	v_pk_mul_f32 v[62:63], v[64:65], v[62:63] op_sel_hi:[0,1]
	v_cvt_pk_bf16_f32 v60, v60, v61
	v_cvt_pk_bf16_f32 v61, v62, v63
	v_lshlrev_b32_e32 v62, 16, v38
	v_and_b32_e32 v63, 0xffff0000, v38
	v_lshlrev_b32_e32 v66, 16, v39
	v_and_b32_e32 v67, 0xffff0000, v39
	v_pk_mul_f32 v[62:63], v[64:65], v[62:63] op_sel_hi:[0,1]
	v_pk_mul_f32 v[64:65], v[64:65], v[66:67] op_sel_hi:[0,1]
	v_cvt_pk_bf16_f32 v62, v62, v63
	v_cvt_pk_bf16_f32 v63, v64, v65
	ds_write_b128 v69, v[36:39]
	ds_write_b128 v69, v[60:63] offset:18432
	ds_read_b32 v64, v68 offset:1280
	s_waitcnt vmcnt(4)
	v_lshlrev_b32_e32 v60, 16, v40
	v_and_b32_e32 v61, 0xffff0000, v40
	v_lshlrev_b32_e32 v62, 16, v41
	v_and_b32_e32 v63, 0xffff0000, v41
	s_waitcnt lgkmcnt(0)
	v_pk_mul_f32 v[60:61], v[64:65], v[60:61] op_sel_hi:[0,1]
	v_pk_mul_f32 v[62:63], v[64:65], v[62:63] op_sel_hi:[0,1]
	v_cvt_pk_bf16_f32 v60, v60, v61
	v_cvt_pk_bf16_f32 v61, v62, v63
	v_lshlrev_b32_e32 v62, 16, v42
	v_and_b32_e32 v63, 0xffff0000, v42
	v_lshlrev_b32_e32 v66, 16, v43
	v_and_b32_e32 v67, 0xffff0000, v43
	v_pk_mul_f32 v[62:63], v[64:65], v[62:63] op_sel_hi:[0,1]
	v_pk_mul_f32 v[64:65], v[64:65], v[66:67] op_sel_hi:[0,1]
	v_cvt_pk_bf16_f32 v62, v62, v63
	v_cvt_pk_bf16_f32 v63, v64, v65
	ds_write_b128 v69, v[40:43] offset:9216
	ds_write_b128 v69, v[60:63] offset:27648
	s_waitcnt lgkmcnt(0)
	s_barrier
	ds_read_b32 v220, v3
	ds_read_b128 v[72:75], v76
	ds_read_b128 v[68:71], v76 offset:64
	ds_read_b128 v[64:67], v76 offset:128
	ds_read_b128 v[60:63], v76 offset:192
	v_cndmask_b32_e64 v3, 0, 1, s[2:3]
	v_cmp_ne_u32_e64 s[18:19], 1, v3
	s_andn2_b64 vcc, exec, s[2:3]
	v_mov_b32_e32 v76, 0
	v_mov_b32_e32 v77, 0
	v_mov_b32_e32 v78, 0
	v_mov_b32_e32 v79, 0
	v_readlane_b32 s21, v234, 1
	s_cbranch_vccnz .LBB0_1843
	ds_read_b128 v[76:79], v2
	ds_read_b128 v[80:83], v2 offset:64
	ds_read_b128 v[236:239], v2 offset:128
	ds_read_b128 v[240:243], v2 offset:192
	s_waitcnt lgkmcnt(3)
	v_mfma_f32_16x16x32_bf16 v[76:79], v[76:79], v[72:75], 0
	s_waitcnt lgkmcnt(2)
	v_mfma_f32_16x16x32_bf16 v[76:79], v[80:83], v[68:71], v[76:79]
	s_waitcnt lgkmcnt(1)
	v_mfma_f32_16x16x32_bf16 v[76:79], v[236:239], v[64:67], v[76:79]
	s_waitcnt lgkmcnt(0)
	v_mfma_f32_16x16x32_bf16 v[76:79], v[240:243], v[60:63], v[76:79]
.LBB0_1843:
	ds_read_b128 v[100:103], v1
	ds_read_b128 v[96:99], v1 offset:512
	v_mov_b32_e32 v80, 0
	s_andn2_b64 vcc, exec, s[34:35]
	v_mov_b32_e32 v92, 0
	v_mov_b32_e32 v93, 0
	v_mov_b32_e32 v94, 0
	v_mov_b32_e32 v95, 0
	s_cbranch_vccnz .LBB0_1845
	ds_read_b128 v[82:85], v2 offset:4352
	ds_read_b128 v[86:89], v2 offset:4416
	ds_read_b128 v[236:239], v2 offset:4480
	ds_read_b128 v[240:243], v2 offset:4544
	s_waitcnt lgkmcnt(3)
	v_mfma_f32_16x16x32_bf16 v[82:85], v[82:85], v[72:75], 0
	s_waitcnt lgkmcnt(2)
	v_mfma_f32_16x16x32_bf16 v[82:85], v[86:89], v[68:71], v[82:85]
	s_waitcnt lgkmcnt(1)
	v_mfma_f32_16x16x32_bf16 v[82:85], v[236:239], v[64:67], v[82:85]
	s_waitcnt lgkmcnt(0)
	v_mfma_f32_16x16x32_bf16 v[92:95], v[240:243], v[60:63], v[82:85]
.LBB0_1845:
	ds_read_b128 v[120:123], v1 offset:64
	ds_read_b128 v[116:119], v1 offset:576
	v_cndmask_b32_e64 v3, 0, 1, s[48:49]
	v_cmp_ne_u32_e64 s[20:21], 1, v3
	s_andn2_b64 vcc, exec, s[48:49]
	v_mov_b32_e32 v81, 0
	v_mov_b32_e32 v82, 0
	v_mov_b32_e32 v83, 0
	s_cbranch_vccnz .LBB0_1847
	ds_read_b128 v[80:83], v2 offset:8704
	ds_read_b128 v[84:87], v2 offset:8768
	ds_read_b128 v[236:239], v2 offset:8832
	ds_read_b128 v[240:243], v2 offset:8896
	s_waitcnt lgkmcnt(3)
	v_mfma_f32_16x16x32_bf16 v[80:83], v[80:83], v[72:75], 0
	s_waitcnt lgkmcnt(2)
	v_mfma_f32_16x16x32_bf16 v[80:83], v[84:87], v[68:71], v[80:83]
	s_waitcnt lgkmcnt(1)
	v_mfma_f32_16x16x32_bf16 v[80:83], v[236:239], v[64:67], v[80:83]
	s_waitcnt lgkmcnt(0)
	v_mfma_f32_16x16x32_bf16 v[80:83], v[240:243], v[60:63], v[80:83]
.LBB0_1847:
	ds_read_b128 v[112:115], v1 offset:128
	ds_read_b128 v[104:107], v1 offset:640
	v_mov_b32_e32 v84, 0
	s_andn2_b64 vcc, exec, s[62:63]
	v_mov_b32_e32 v108, 0
	v_mov_b32_e32 v109, 0
	v_mov_b32_e32 v110, 0
	v_mov_b32_e32 v111, 0
	s_cbranch_vccnz .LBB0_1849
	ds_read_b128 v[86:89], v2 offset:13056
	ds_read_b128 v[108:111], v2 offset:13120
	ds_read_b128 v[236:239], v2 offset:13184
	ds_read_b128 v[240:243], v2 offset:13248
	s_waitcnt lgkmcnt(3)
	v_mfma_f32_16x16x32_bf16 v[86:89], v[86:89], v[72:75], 0
	s_waitcnt lgkmcnt(2)
	v_mfma_f32_16x16x32_bf16 v[86:89], v[108:111], v[68:71], v[86:89]
	s_waitcnt lgkmcnt(1)
	v_mfma_f32_16x16x32_bf16 v[86:89], v[236:239], v[64:67], v[86:89]
	s_waitcnt lgkmcnt(0)
	v_mfma_f32_16x16x32_bf16 v[108:111], v[240:243], v[60:63], v[86:89]
.LBB0_1849:
	ds_read_b128 v[140:143], v1 offset:192
	ds_read_b128 v[132:135], v1 offset:704
	v_cndmask_b32_e64 v3, 0, 1, s[72:73]
	v_cmp_ne_u32_e64 s[22:23], 1, v3
	s_andn2_b64 vcc, exec, s[72:73]
	v_mov_b32_e32 v85, 0
	v_mov_b32_e32 v86, 0
	v_mov_b32_e32 v87, 0
	s_cbranch_vccnz .LBB0_1851
	ds_read_b128 v[84:87], v2 offset:17408
	ds_read_b128 v[88:91], v2 offset:17472
	ds_read_b128 v[236:239], v2 offset:17536
	ds_read_b128 v[240:243], v2 offset:17600
	s_waitcnt lgkmcnt(3)
	v_mfma_f32_16x16x32_bf16 v[84:87], v[84:87], v[72:75], 0
	s_waitcnt lgkmcnt(2)
	v_mfma_f32_16x16x32_bf16 v[84:87], v[88:91], v[68:71], v[84:87]
	s_waitcnt lgkmcnt(1)
	v_mfma_f32_16x16x32_bf16 v[84:87], v[236:239], v[64:67], v[84:87]
	s_waitcnt lgkmcnt(0)
	v_mfma_f32_16x16x32_bf16 v[84:87], v[240:243], v[60:63], v[84:87]
.LBB0_1851:
	ds_read_b128 v[136:139], v1 offset:256
	ds_read_b128 v[124:127], v1 offset:768
	v_mov_b32_e32 v88, 0
	s_andn2_b64 vcc, exec, s[82:83]
	v_mov_b32_e32 v128, 0
	v_mov_b32_e32 v129, 0
	v_mov_b32_e32 v130, 0
	v_mov_b32_e32 v131, 0
	s_cbranch_vccnz .LBB0_1853
	ds_read_b128 v[128:131], v2 offset:21760
	ds_read_b128 v[144:147], v2 offset:21824
	ds_read_b128 v[236:239], v2 offset:21888
	ds_read_b128 v[240:243], v2 offset:21952
	s_waitcnt lgkmcnt(3)
	v_mfma_f32_16x16x32_bf16 v[128:131], v[128:131], v[72:75], 0
	s_waitcnt lgkmcnt(2)
	v_mfma_f32_16x16x32_bf16 v[128:131], v[144:147], v[68:71], v[128:131]
	s_waitcnt lgkmcnt(1)
	v_mfma_f32_16x16x32_bf16 v[128:131], v[236:239], v[64:67], v[128:131]
	s_waitcnt lgkmcnt(0)
	v_mfma_f32_16x16x32_bf16 v[128:131], v[240:243], v[60:63], v[128:131]
.LBB0_1853:
	ds_read_b128 v[160:163], v1 offset:320
	ds_read_b128 v[152:155], v1 offset:832
	v_cndmask_b32_e64 v3, 0, 1, s[92:93]
	v_cmp_ne_u32_e64 s[24:25], 1, v3
	s_andn2_b64 vcc, exec, s[92:93]
	v_mov_b32_e32 v89, 0
	v_mov_b32_e32 v90, 0
	v_mov_b32_e32 v91, 0
	s_cbranch_vccnz .LBB0_1855
	ds_read_b128 v[88:91], v2 offset:26112
	ds_read_b128 v[144:147], v2 offset:26176
	ds_read_b128 v[236:239], v2 offset:26240
	ds_read_b128 v[240:243], v2 offset:26304
	s_waitcnt lgkmcnt(3)
	v_mfma_f32_16x16x32_bf16 v[88:91], v[88:91], v[72:75], 0
	s_waitcnt lgkmcnt(2)
	v_mfma_f32_16x16x32_bf16 v[88:91], v[144:147], v[68:71], v[88:91]
	s_waitcnt lgkmcnt(1)
	v_mfma_f32_16x16x32_bf16 v[88:91], v[236:239], v[64:67], v[88:91]
	s_waitcnt lgkmcnt(0)
	v_mfma_f32_16x16x32_bf16 v[88:91], v[240:243], v[60:63], v[88:91]
.LBB0_1855:
	ds_read_b128 v[156:159], v1 offset:384
	ds_read_b128 v[148:151], v1 offset:896
	v_mov_b32_e32 v144, 0
	s_andn2_b64 vcc, exec, s[10:11]
	v_mov_b32_e32 v145, 0
	v_mov_b32_e32 v146, 0
	v_mov_b32_e32 v147, 0
	s_cbranch_vccnz .LBB0_1857
	ds_read_b128 v[144:147], v2 offset:30464
	ds_read_b128 v[222:225], v2 offset:30528
	ds_read_b128 v[236:239], v2 offset:30592
	ds_read_b128 v[240:243], v2 offset:30656
	s_waitcnt lgkmcnt(3)
	v_mfma_f32_16x16x32_bf16 v[144:147], v[144:147], v[72:75], 0
	s_waitcnt lgkmcnt(2)
	v_mfma_f32_16x16x32_bf16 v[144:147], v[222:225], v[68:71], v[144:147]
	s_waitcnt lgkmcnt(1)
	v_mfma_f32_16x16x32_bf16 v[144:147], v[236:239], v[64:67], v[144:147]
	s_waitcnt lgkmcnt(0)
	v_mfma_f32_16x16x32_bf16 v[144:147], v[240:243], v[60:63], v[144:147]

.LBB0_1918:
	s_or_b64 exec, exec, s[24:25]
	v_mov_b32_e32 v3, s33
	s_waitcnt lgkmcnt(0)
	s_barrier
	s_waitcnt vmcnt(0)
	ds_read_b32 v229, v228 offset:1024
	ds_read_b32 v230, v3 offset:2056
	v_cndmask_b32_e64 v3, 0, 1, s[64:65]
	v_mov_b32_e32 v118, 0
	v_cmp_ne_u32_e64 s[24:25], 1, v3
	s_andn2_b64 vcc, exec, s[64:65]
	v_mov_b32_e32 v122, 0
	v_mov_b32_e32 v123, 0
	v_mov_b32_e32 v124, 0
	v_mov_b32_e32 v125, 0
	s_cbranch_vccnz .LBB0_1920
	ds_read_b128 v[120:123], v2
	ds_read_b128 v[124:127], v2 offset:64
	ds_read_b128 v[236:239], v2 offset:128
	ds_read_b128 v[240:243], v2 offset:192
	ds_read_b128 v[244:247], v2 offset:256
	ds_read_b128 v[248:251], v2 offset:320
	ds_read_b128 v[252:255], v2 offset:384
	s_waitcnt lgkmcnt(6)
	v_mfma_f32_16x16x32_bf16 v[120:123], v[120:123], v[44:47], 0
	s_waitcnt lgkmcnt(5)
	v_mfma_f32_16x16x32_bf16 v[120:123], v[124:127], v[48:51], v[120:123]
	ds_read_b128 v[124:127], v2 offset:448
	s_waitcnt lgkmcnt(5)
	v_mfma_f32_16x16x32_bf16 v[120:123], v[236:239], v[52:55], v[120:123]
	s_waitcnt lgkmcnt(4)
	v_mfma_f32_16x16x32_bf16 v[120:123], v[240:243], v[56:59], v[120:123]
	s_waitcnt lgkmcnt(3)
	v_mfma_f32_16x16x32_bf16 v[120:123], v[244:247], v[60:63], v[120:123]
	s_waitcnt lgkmcnt(2)
	v_mfma_f32_16x16x32_bf16 v[120:123], v[248:251], v[64:67], v[120:123]
	s_waitcnt lgkmcnt(1)
	v_mfma_f32_16x16x32_bf16 v[120:123], v[252:255], v[68:71], v[120:123]
	s_waitcnt lgkmcnt(0)
	v_mfma_f32_16x16x32_bf16 v[122:125], v[124:127], v[72:75], v[120:123]
.LBB0_1920:
	s_cmp_lg_u32 s48, 15
	s_cbranch_scc0 .Lmlpf_skip0
	v_readlane_b32 s100, v234, 2
	v_readlane_b32 s101, v234, 3
	s_add_u32 s100, s100, 0x1aca0000
	s_addc_u32 s101, s101, 0
	v_lshl_add_u64 v[24:25], v[200:201], 0, s[100:101]
	global_load_dwordx4 v[24:27], v[24:25], off offset:2048
	s_add_u32 s100, s100, 0x74000
	s_addc_u32 s101, s101, 0
	v_lshl_add_u64 v[4:5], v[200:201], 0, s[100:101]
	global_load_dwordx4 v[4:7], v[4:5], off offset:2048
.Lmlpf_skip0:
	ds_read_b128 v[126:129], v1
	v_readlane_b32 s26, v232, 2
	v_readlane_b32 s27, v232, 3
	s_andn2_b64 vcc, exec, s[26:27]
	v_mov_b32_e32 v119, 0
	v_mov_b32_e32 v120, 0
	v_mov_b32_e32 v121, 0
	s_cbranch_vccnz .LBB0_1922
	ds_read_b128 v[116:119], v2 offset:8448
	ds_read_b128 v[130:133], v2 offset:8512
	ds_read_b128 v[236:239], v2 offset:8576
	ds_read_b128 v[240:243], v2 offset:8640
	ds_read_b128 v[244:247], v2 offset:8704
	ds_read_b128 v[248:251], v2 offset:8768
	ds_read_b128 v[252:255], v2 offset:8832
	s_waitcnt lgkmcnt(6)
	v_mfma_f32_16x16x32_bf16 v[116:119], v[116:119], v[44:47], 0
	s_waitcnt lgkmcnt(5)
	v_mfma_f32_16x16x32_bf16 v[116:119], v[130:133], v[48:51], v[116:119]
	ds_read_b128 v[130:133], v2 offset:8896
	s_waitcnt lgkmcnt(5)
	v_mfma_f32_16x16x32_bf16 v[116:119], v[236:239], v[52:55], v[116:119]
	s_waitcnt lgkmcnt(4)
	v_mfma_f32_16x16x32_bf16 v[116:119], v[240:243], v[56:59], v[116:119]
	s_waitcnt lgkmcnt(3)
	v_mfma_f32_16x16x32_bf16 v[116:119], v[244:247], v[60:63], v[116:119]
	s_waitcnt lgkmcnt(2)
	v_mfma_f32_16x16x32_bf16 v[116:119], v[248:251], v[64:67], v[116:119]
	s_waitcnt lgkmcnt(1)
	v_mfma_f32_16x16x32_bf16 v[116:119], v[252:255], v[68:71], v[116:119]
	s_waitcnt lgkmcnt(0)
	v_mfma_f32_16x16x32_bf16 v[118:121], v[130:133], v[72:75], v[116:119]
.LBB0_1922:
	s_cmp_lg_u32 s48, 15
	s_cbranch_scc0 .Lmlpf_skip1
	v_readlane_b32 s100, v234, 2
	v_readlane_b32 s101, v234, 3
	s_add_u32 s100, s100, 0x1ad88000
	s_addc_u32 s101, s101, 0
	v_lshl_add_u64 v[8:9], v[200:201], 0, s[100:101]
	global_load_dwordx4 v[8:11], v[8:9], off offset:2048
	s_add_u32 s100, s100, 0x74000
	s_addc_u32 s101, s101, 0
	v_lshl_add_u64 v[12:13], v[200:201], 0, s[100:101]
	global_load_dwordx4 v[12:15], v[12:13], off offset:2048
.Lmlpf_skip1:
	ds_read_b128 v[134:137], v1 offset:64
	v_cndmask_b32_e64 v3, 0, 1, s[74:75]
	v_mov_b32_e32 v130, 0
	v_cmp_ne_u32_e64 s[26:27], 1, v3
	s_andn2_b64 vcc, exec, s[74:75]
	v_mov_b32_e32 v138, 0
	v_mov_b32_e32 v139, 0
	v_mov_b32_e32 v140, 0
	v_mov_b32_e32 v141, 0
	s_cbranch_vccnz .LBB0_1924
	ds_read_b128 v[138:141], v2 offset:16896
	ds_read_b128 v[142:145], v2 offset:16960
	ds_read_b128 v[236:239], v2 offset:17024
	ds_read_b128 v[240:243], v2 offset:17088
	ds_read_b128 v[244:247], v2 offset:17152
	ds_read_b128 v[248:251], v2 offset:17216
	ds_read_b128 v[252:255], v2 offset:17280
	s_waitcnt lgkmcnt(6)
	v_mfma_f32_16x16x32_bf16 v[138:141], v[138:141], v[44:47], 0
	s_waitcnt lgkmcnt(5)
	v_mfma_f32_16x16x32_bf16 v[138:141], v[142:145], v[48:51], v[138:141]
	ds_read_b128 v[142:145], v2 offset:17344
	s_waitcnt lgkmcnt(5)
	v_mfma_f32_16x16x32_bf16 v[138:141], v[236:239], v[52:55], v[138:141]
	s_waitcnt lgkmcnt(4)
	v_mfma_f32_16x16x32_bf16 v[138:141], v[240:243], v[56:59], v[138:141]
	s_waitcnt lgkmcnt(3)
	v_mfma_f32_16x16x32_bf16 v[138:141], v[244:247], v[60:63], v[138:141]
	s_waitcnt lgkmcnt(2)
	v_mfma_f32_16x16x32_bf16 v[138:141], v[248:251], v[64:67], v[138:141]
	s_waitcnt lgkmcnt(1)
	v_mfma_f32_16x16x32_bf16 v[138:141], v[252:255], v[68:71], v[138:141]
	s_waitcnt lgkmcnt(0)
	v_mfma_f32_16x16x32_bf16 v[138:141], v[142:145], v[72:75], v[138:141]
.LBB0_1924:
	s_cmp_lg_u32 s48, 15
	s_cbranch_scc0 .Lmlpf_skip2
	v_readlane_b32 s100, v234, 2
	v_readlane_b32 s101, v234, 3
	s_add_u32 s100, s100, 0x1ae70000
	s_addc_u32 s101, s101, 0
	v_lshl_add_u64 v[16:17], v[200:201], 0, s[100:101]
	global_load_dwordx4 v[16:19], v[16:17], off offset:2048
	s_add_u32 s100, s100, 0x74000
	s_addc_u32 s101, s101, 0
	v_lshl_add_u64 v[20:21], v[200:201], 0, s[100:101]
	global_load_dwordx4 v[20:23], v[20:21], off offset:2048
.Lmlpf_skip2:
	ds_read_b128 v[142:145], v1 offset:128
	s_andn2_b64 vcc, exec, s[86:87]
	v_mov_b32_e32 v131, 0
	v_mov_b32_e32 v132, 0
	v_mov_b32_e32 v133, 0
	s_cbranch_vccnz .LBB0_1926
	ds_read_b128 v[130:133], v2 offset:25344
	ds_read_b128 v[146:149], v2 offset:25408
	ds_read_b128 v[236:239], v2 offset:25472
	ds_read_b128 v[240:243], v2 offset:25536
	ds_read_b128 v[244:247], v2 offset:25600
	ds_read_b128 v[248:251], v2 offset:25664
	ds_read_b128 v[252:255], v2 offset:25728
	s_waitcnt lgkmcnt(6)
	v_mfma_f32_16x16x32_bf16 v[130:133], v[130:133], v[44:47], 0
	s_waitcnt lgkmcnt(5)
	v_mfma_f32_16x16x32_bf16 v[130:133], v[146:149], v[48:51], v[130:133]
	ds_read_b128 v[146:149], v2 offset:25792
	s_waitcnt lgkmcnt(5)
	v_mfma_f32_16x16x32_bf16 v[130:133], v[236:239], v[52:55], v[130:133]
	s_waitcnt lgkmcnt(4)
	v_mfma_f32_16x16x32_bf16 v[130:133], v[240:243], v[56:59], v[130:133]
	s_waitcnt lgkmcnt(3)
	v_mfma_f32_16x16x32_bf16 v[130:133], v[244:247], v[60:63], v[130:133]
	s_waitcnt lgkmcnt(2)
	v_mfma_f32_16x16x32_bf16 v[130:133], v[248:251], v[64:67], v[130:133]
	s_waitcnt lgkmcnt(1)
	v_mfma_f32_16x16x32_bf16 v[130:133], v[252:255], v[68:71], v[130:133]
	s_waitcnt lgkmcnt(0)
	v_mfma_f32_16x16x32_bf16 v[130:133], v[146:149], v[72:75], v[130:133]
.LBB0_1926:
	s_cmp_lg_u32 s48, 15
	s_cbranch_scc0 .Lmlpf_skip3
	v_readlane_b32 s100, v234, 2
	v_readlane_b32 s101, v234, 3
	s_add_u32 s100, s100, 0x1af58000
	s_addc_u32 s101, s101, 0
	v_lshl_add_u64 v[28:29], v[200:201], 0, s[100:101]
	global_load_dwordx4 v[28:31], v[28:29], off offset:2048
	s_add_u32 s100, s100, 0x74000
	s_addc_u32 s101, s101, 0
	v_lshl_add_u64 v[32:33], v[200:201], 0, s[100:101]
	global_load_dwordx4 v[32:35], v[32:33], off offset:2048
.Lmlpf_skip3:
	ds_read_b128 v[150:153], v1 offset:192
	v_cndmask_b32_e64 v3, 0, 1, s[58:59]
	v_mov_b32_e32 v146, 0
	v_cmp_ne_u32_e64 s[28:29], 1, v3
	s_andn2_b64 vcc, exec, s[58:59]
	v_mov_b32_e32 v154, 0
	v_mov_b32_e32 v155, 0
	v_mov_b32_e32 v156, 0
	v_mov_b32_e32 v157, 0
	s_cbranch_vccnz .LBB0_1928
	ds_read_b128 v[154:157], v2 offset:33792
	ds_read_b128 v[158:161], v2 offset:33856
	ds_read_b128 v[236:239], v2 offset:33920
	ds_read_b128 v[240:243], v2 offset:33984
	ds_read_b128 v[244:247], v2 offset:34048
	ds_read_b128 v[248:251], v2 offset:34112
	ds_read_b128 v[252:255], v2 offset:34176
	s_waitcnt lgkmcnt(6)
	v_mfma_f32_16x16x32_bf16 v[154:157], v[154:157], v[44:47], 0
	s_waitcnt lgkmcnt(5)
	v_mfma_f32_16x16x32_bf16 v[154:157], v[158:161], v[48:51], v[154:157]
	ds_read_b128 v[158:161], v2 offset:34240
	s_waitcnt lgkmcnt(5)
	v_mfma_f32_16x16x32_bf16 v[154:157], v[236:239], v[52:55], v[154:157]
	s_waitcnt lgkmcnt(4)
	v_mfma_f32_16x16x32_bf16 v[154:157], v[240:243], v[56:59], v[154:157]
	s_waitcnt lgkmcnt(3)
	v_mfma_f32_16x16x32_bf16 v[154:157], v[244:247], v[60:63], v[154:157]
	s_waitcnt lgkmcnt(2)
	v_mfma_f32_16x16x32_bf16 v[154:157], v[248:251], v[64:67], v[154:157]
	s_waitcnt lgkmcnt(1)
	v_mfma_f32_16x16x32_bf16 v[154:157], v[252:255], v[68:71], v[154:157]
	s_waitcnt lgkmcnt(0)
	v_mfma_f32_16x16x32_bf16 v[154:157], v[158:161], v[72:75], v[154:157]
.LBB0_1928:
	s_cmp_lg_u32 s48, 15
	s_cbranch_scc0 .Lmlpf_skip4
	v_readlane_b32 s100, v234, 2
	v_readlane_b32 s101, v234, 3
	s_add_u32 s100, s100, 0x1aca1000
	s_addc_u32 s101, s101, 0
	v_lshl_add_u64 v[40:41], v[202:203], 0, s[100:101]
	global_load_dwordx4 v[40:43], v[40:41], off
	v_lshl_add_u64 v[36:37], v[202:203], 0, s[100:101]
	global_load_dwordx4 v[36:39], v[36:37], off offset:16
.Lmlpf_skip4:
	ds_read_b128 v[158:161], v1 offset:256
	s_andn2_b64 vcc, exec, s[4:5]
	v_mov_b32_e32 v147, 0
	v_mov_b32_e32 v148, 0
	v_mov_b32_e32 v149, 0
	s_cbranch_vccnz .LBB0_1930
	ds_read_b128 v[146:149], v2 offset:42240
	ds_read_b128 v[162:165], v2 offset:42304
	ds_read_b128 v[236:239], v2 offset:42368
	ds_read_b128 v[240:243], v2 offset:42432
	ds_read_b128 v[244:247], v2 offset:42496
	ds_read_b128 v[248:251], v2 offset:42560
	ds_read_b128 v[252:255], v2 offset:42624
	s_waitcnt lgkmcnt(6)
	v_mfma_f32_16x16x32_bf16 v[146:149], v[146:149], v[44:47], 0
	s_waitcnt lgkmcnt(5)
	v_mfma_f32_16x16x32_bf16 v[146:149], v[162:165], v[48:51], v[146:149]
	ds_read_b128 v[162:165], v2 offset:42688
	s_waitcnt lgkmcnt(5)
	v_mfma_f32_16x16x32_bf16 v[146:149], v[236:239], v[52:55], v[146:149]
	s_waitcnt lgkmcnt(4)
	v_mfma_f32_16x16x32_bf16 v[146:149], v[240:243], v[56:59], v[146:149]
	s_waitcnt lgkmcnt(3)
	v_mfma_f32_16x16x32_bf16 v[146:149], v[244:247], v[60:63], v[146:149]
	s_waitcnt lgkmcnt(2)
	v_mfma_f32_16x16x32_bf16 v[146:149], v[248:251], v[64:67], v[146:149]
	s_waitcnt lgkmcnt(1)
	v_mfma_f32_16x16x32_bf16 v[146:149], v[252:255], v[68:71], v[146:149]
	s_waitcnt lgkmcnt(0)
	v_mfma_f32_16x16x32_bf16 v[146:149], v[162:165], v[72:75], v[146:149]
.LBB0_1930:
	ds_read_b128 v[166:169], v1 offset:320
	v_cndmask_b32_e64 v3, 0, 1, s[94:95]
	v_mov_b32_e32 v162, 0
	v_cmp_ne_u32_e64 s[30:31], 1, v3
	s_andn2_b64 vcc, exec, s[94:95]
	v_mov_b32_e32 v170, 0
	v_mov_b32_e32 v171, 0
	v_mov_b32_e32 v172, 0
	v_mov_b32_e32 v173, 0
	s_cbranch_vccnz .LBB0_1932
	ds_read_b128 v[170:173], v2 offset:50688
	ds_read_b128 v[174:177], v2 offset:50752
	ds_read_b128 v[236:239], v2 offset:50816
	ds_read_b128 v[240:243], v2 offset:50880
	ds_read_b128 v[244:247], v2 offset:50944
	ds_read_b128 v[248:251], v2 offset:51008
	ds_read_b128 v[252:255], v2 offset:51072
	s_waitcnt lgkmcnt(6)
	v_mfma_f32_16x16x32_bf16 v[170:173], v[170:173], v[44:47], 0
	s_waitcnt lgkmcnt(5)
	v_mfma_f32_16x16x32_bf16 v[170:173], v[174:177], v[48:51], v[170:173]
	ds_read_b128 v[174:177], v2 offset:51136
	s_waitcnt lgkmcnt(5)
	v_mfma_f32_16x16x32_bf16 v[170:173], v[236:239], v[52:55], v[170:173]
	s_waitcnt lgkmcnt(4)
	v_mfma_f32_16x16x32_bf16 v[170:173], v[240:243], v[56:59], v[170:173]
	s_waitcnt lgkmcnt(3)
	v_mfma_f32_16x16x32_bf16 v[170:173], v[244:247], v[60:63], v[170:173]
	s_waitcnt lgkmcnt(2)
	v_mfma_f32_16x16x32_bf16 v[170:173], v[248:251], v[64:67], v[170:173]
	s_waitcnt lgkmcnt(1)
	v_mfma_f32_16x16x32_bf16 v[170:173], v[252:255], v[68:71], v[170:173]
	s_waitcnt lgkmcnt(0)
	v_mfma_f32_16x16x32_bf16 v[170:173], v[174:177], v[72:75], v[170:173]
.LBB0_1932:
	ds_read_b128 v[174:177], v1 offset:384
	s_andn2_b64 vcc, exec, s[66:67]
	v_mov_b32_e32 v163, 0
	v_mov_b32_e32 v164, 0
	v_mov_b32_e32 v165, 0
	s_cbranch_vccnz .LBB0_1934
	ds_read_b128 v[162:165], v2 offset:59136
	ds_read_b128 v[178:181], v2 offset:59200
	ds_read_b128 v[236:239], v2 offset:59264
	ds_read_b128 v[240:243], v2 offset:59328
	ds_read_b128 v[244:247], v2 offset:59392
	ds_read_b128 v[248:251], v2 offset:59456
	ds_read_b128 v[252:255], v2 offset:59520
	s_waitcnt lgkmcnt(6)
	v_mfma_f32_16x16x32_bf16 v[162:165], v[162:165], v[44:47], 0
	s_waitcnt lgkmcnt(5)
	v_mfma_f32_16x16x32_bf16 v[162:165], v[178:181], v[48:51], v[162:165]
	ds_read_b128 v[178:181], v2 offset:59584
	s_waitcnt lgkmcnt(5)
	v_mfma_f32_16x16x32_bf16 v[162:165], v[236:239], v[52:55], v[162:165]
	s_waitcnt lgkmcnt(4)
	v_mfma_f32_16x16x32_bf16 v[162:165], v[240:243], v[56:59], v[162:165]
	s_waitcnt lgkmcnt(3)
	v_mfma_f32_16x16x32_bf16 v[162:165], v[244:247], v[60:63], v[162:165]
	s_waitcnt lgkmcnt(2)
	v_mfma_f32_16x16x32_bf16 v[162:165], v[248:251], v[64:67], v[162:165]
	s_waitcnt lgkmcnt(1)
	v_mfma_f32_16x16x32_bf16 v[162:165], v[252:255], v[68:71], v[162:165]
	s_waitcnt lgkmcnt(0)
	v_mfma_f32_16x16x32_bf16 v[162:165], v[178:181], v[72:75], v[162:165]

.LBB0_1943:
	s_nop 7
	ds_read_b128 v[136:139], v184 offset:33792
	ds_read_b128 v[140:143], v184 offset:33856
	ds_read_b128 v[144:147], v184 offset:33920
	v_and_b32_e32 v1, 64, v210
	v_or_b32_e32 v2, v1, v212
	s_waitcnt lgkmcnt(2)
	v_mfma_f32_16x16x32_bf16 v[136:139], v[136:139], v[44:47], 0
	v_lshlrev_b32_e32 v3, 2, v2
	ds_bpermute_b32 v2, v3, v134
	s_mov_b32 s54, s52
	s_waitcnt lgkmcnt(2)
	v_mfma_f32_16x16x32_bf16 v[136:139], v[140:143], v[48:51], v[136:139]
	ds_read_b128 v[140:143], v184 offset:33984
	s_mov_b32 s55, s52
	s_mov_b32 s53, s52
	s_waitcnt lgkmcnt(2)
	v_mfma_f32_16x16x32_bf16 v[136:139], v[144:147], v[52:55], v[136:139]
	ds_read_b128 v[144:147], v184 offset:34048
	s_and_b64 vcc, exec, s[24:25]
	s_waitcnt lgkmcnt(1)
	v_mfma_f32_16x16x32_bf16 v[136:139], v[140:143], v[56:59], v[136:139]
	ds_read_b128 v[140:143], v184 offset:34112
	s_waitcnt lgkmcnt(1)
	v_mfma_f32_16x16x32_bf16 v[136:139], v[144:147], v[60:63], v[136:139]
	ds_read_b128 v[144:147], v184 offset:34176
	s_waitcnt lgkmcnt(1)
	v_mfma_f32_16x16x32_bf16 v[136:139], v[140:143], v[64:67], v[136:139]
	ds_read_b128 v[140:143], v184 offset:34240
	s_waitcnt lgkmcnt(1)
	v_mfma_f32_16x16x32_bf16 v[136:139], v[144:147], v[68:71], v[136:139]
	s_waitcnt lgkmcnt(0)
	v_mfma_f32_16x16x32_bf16 v[136:139], v[140:143], v[72:75], v[136:139]
	s_nop 7
	ds_bpermute_b32 v132, v3, v136
	ds_read_b32 v3, v228 offset:512
	v_mov_b64_e32 v[138:139], s[54:55]
	v_mov_b64_e32 v[136:137], s[52:53]
	s_cbranch_vccz .LBB0_1981
	s_and_b64 vcc, exec, s[26:27]
	s_cbranch_vccz .LBB0_1982

.LBB0_1971:
	s_andn2_b64 vcc, exec, s[24:25]
	s_waitcnt lgkmcnt(0)
	s_barrier
	s_cbranch_vccnz .LBB0_1973
	v_readlane_b32 s24, v234, 0
	v_readlane_b32 s26, v234, 2
	v_readlane_b32 s27, v234, 3
	v_readlane_b32 s25, v234, 1
	v_lshl_add_u64 v[2:3], s[26:27], 0, v[204:205]
	global_load_dwordx4 v[44:47], v[2:3], off offset:-256
	global_load_dwordx4 v[48:51], v[2:3], off offset:-192
	global_load_dwordx4 v[52:55], v[2:3], off offset:-128
	global_load_dwordx4 v[56:59], v[2:3], off offset:-64
	global_load_dwordx4 v[60:63], v[2:3], off
	global_load_dwordx4 v[64:67], v[2:3], off offset:64
	global_load_dwordx4 v[68:71], v[2:3], off offset:128
	global_load_dwordx4 v[72:75], v[2:3], off offset:192

	.amdhsa_kernel _Z10hybrid_fwd4Args
		.amdhsa_group_segment_fixed_size 0
		.amdhsa_private_segment_fixed_size 0
		.amdhsa_kernarg_size 496
		.amdhsa_user_sgpr_count 2
		.amdhsa_user_sgpr_dispatch_ptr 0
		.amdhsa_user_sgpr_queue_ptr 0
		.amdhsa_user_sgpr_kernarg_segment_ptr 1
		.amdhsa_user_sgpr_dispatch_id 0
		.amdhsa_user_sgpr_kernarg_preload_length 0
		.amdhsa_user_sgpr_kernarg_preload_offset 0
		.amdhsa_user_sgpr_private_segment_size 0
		.amdhsa_uses_dynamic_stack 0
		.amdhsa_enable_private_segment 0
		.amdhsa_system_sgpr_workgroup_id_x 1
		.amdhsa_system_sgpr_workgroup_id_y 0
		.amdhsa_system_sgpr_workgroup_id_z 0
		.amdhsa_system_sgpr_workgroup_info 0
		.amdhsa_system_vgpr_workitem_id 2
		.amdhsa_next_free_vgpr 256
		.amdhsa_next_free_sgpr 102
		.amdhsa_accum_offset 256
		.amdhsa_reserve_vcc 1
		.amdhsa_float_round_mode_32 0
		.amdhsa_float_round_mode_16_64 0
		.amdhsa_float_denorm_mode_32 3
		.amdhsa_float_denorm_mode_16_64 3
		.amdhsa_dx10_clamp 1
		.amdhsa_ieee_mode 1
		.amdhsa_fp16_overflow 0
		.amdhsa_tg_split 0
		.amdhsa_exception_fp_ieee_invalid_op 0
		.amdhsa_exception_fp_denorm_src 0
		.amdhsa_exception_fp_ieee_div_zero 0
		.amdhsa_exception_fp_ieee_overflow 0
		.amdhsa_exception_fp_ieee_underflow 0
		.amdhsa_exception_fp_ieee_inexact 0
		.amdhsa_exception_int_div_zero 0
	.end_amdhsa_kernel

amdhsa.kernels:
  - .agpr_count:     0
    .args:
      - .offset:         0
        .size:           240
        .value_kind:     by_value
      - .offset:         240
        .size:           4
        .value_kind:     hidden_block_count_x
      - .offset:         244
        .size:           4
        .value_kind:     hidden_block_count_y
      - .offset:         248
        .size:           4
        .value_kind:     hidden_block_count_z
      - .offset:         252
        .size:           2
        .value_kind:     hidden_group_size_x
      - .offset:         254
        .size:           2
        .value_kind:     hidden_group_size_y
      - .offset:         256
        .size:           2
        .value_kind:     hidden_group_size_z
      - .offset:         258
        .size:           2
        .value_kind:     hidden_remainder_x
      - .offset:         260
        .size:           2
        .value_kind:     hidden_remainder_y
      - .offset:         262
        .size:           2
        .value_kind:     hidden_remainder_z
      - .offset:         280
        .size:           8
        .value_kind:     hidden_global_offset_x
      - .offset:         288
        .size:           8
        .value_kind:     hidden_global_offset_y
      - .offset:         296
        .size:           8
        .value_kind:     hidden_global_offset_z
      - .offset:         304
        .size:           2
        .value_kind:     hidden_grid_dims
      - .offset:         328
        .size:           8
        .value_kind:     hidden_multigrid_sync_arg
      - .offset:         360
        .size:           4
        .value_kind:     hidden_dynamic_lds_size
    .group_segment_fixed_size: 0
    .kernarg_segment_align: 8
    .kernarg_segment_size: 496
    .language:       OpenCL C
    .language_version:
      - 2
      - 0
    .max_flat_workgroup_size: 512
    .name:           _Z10hybrid_fwd4Args
    .private_segment_fixed_size: 0
    .sgpr_count:     108
    .sgpr_spill_count: 170
    .symbol:         _Z10hybrid_fwd4Args.kd
    .uniform_work_group_size: 1
    .uses_dynamic_stack: false
    .vgpr_count:     256
    .vgpr_spill_count: 0
    .wavefront_size: 64
